# speedup vs baseline: 1.0122x; 1.0056x over previous
.LBB0_850:
	v_lshl_add_u32 v164, s28, 8, v149
	v_ashrrev_i32_e32 v165, 31, v164
	v_lshl_add_u64 v[146:147], v[164:165], 2, s[66:67]
	v_mov_b32_e32 v166, v233
	v_or_b32_e32 v176, 16, v164
	v_ashrrev_i32_e32 v177, 31, v176
	v_mov_b32_e32 v174, v118
	v_mov_b32_e32 v175, v114
	v_mov_b32_e32 v114, v119
	v_lshl_add_u64 v[118:119], v[176:177], 2, s[66:67]
	v_mov_b32_e32 v180, v234
	v_or_b32_e32 v158, 32, v164
	v_add_u32_e32 v150, 0x80, v164
	v_mov_b32_e32 v168, v124
	v_mov_b32_e32 v169, v120
	v_mov_b32_e32 v172, v116
	v_or_b32_e32 v154, 48, v164
	v_add_u32_e32 v146, 0x90, v164
	v_add_u32_e32 v124, 0xa0, v164
	v_add_u32_e32 v116, 0xb0, v164
	v_ashrrev_i32_e32 v159, 31, v158
	v_ashrrev_i32_e32 v151, 31, v150
	v_mov_b32_e32 v120, v125
	v_mov_b32_e32 v170, v126
	v_mov_b32_e32 v171, v122
	v_mov_b32_e32 v122, v127
	v_mov_b32_e32 v173, v112
	v_mov_b32_e32 v112, v117
	v_ashrrev_i32_e32 v155, 31, v154
	v_ashrrev_i32_e32 v147, 31, v146
	v_ashrrev_i32_e32 v125, 31, v124
	v_ashrrev_i32_e32 v117, 31, v116
	v_lshl_add_u64 v[126:127], v[158:159], 2, s[66:67]
	v_lshl_add_u64 v[118:119], v[150:151], 2, s[66:67]
	v_lshl_add_u64 v[178:179], v[154:155], 2, s[66:67]
	v_lshl_add_u64 v[182:183], v[146:147], 2, s[66:67]
	v_lshl_add_u64 v[184:185], v[124:125], 2, s[66:67]
	v_lshl_add_u64 v[188:189], v[116:117], 2, s[66:67]
	v_mov_b32_e32 v160, v235
	v_mov_b32_e32 v156, v236
	v_mov_b32_e32 v152, v237
	v_mov_b32_e32 v148, v238
	s_nop 0
	v_mov_b32_e32 v126, v239
	v_mov_b32_e32 v118, v240
	s_cmp_lg_u64 s[4:5], 0
	s_cselect_b32 s92, s22, s28
	v_lshl_add_u32 v232, s92, 8, v149
	v_lshlrev_b32_e32 v232, 2, v232
	global_load_dword v233, v232, s[66:67]
	global_load_dword v234, v232, s[66:67] offset:64
	global_load_dword v235, v232, s[66:67] offset:128
	global_load_dword v236, v232, s[66:67] offset:192
	global_load_dword v237, v232, s[66:67] offset:512
	global_load_dword v238, v232, s[66:67] offset:576
	global_load_dword v239, v232, s[66:67] offset:640
	global_load_dword v240, v232, s[66:67] offset:704
	v_mov_b32_e32 v165, v108
	v_mov_b32_e32 v108, v105
	s_lshl_b32 s28, s29, 7
	s_ashr_i32 s29, s28, 31
	s_lshl_b64 s[28:29], s[28:29], 1
	s_andn2_b64 vcc, exec, s[4:5]
	s_mov_b64 s[4:5], -1
	v_pk_mul_f32 v[168:169], v[168:169], v[166:167] op_sel_hi:[1,0]
	v_pk_mul_f32 v[120:121], v[120:121], v[166:167] op_sel_hi:[1,0]
	v_mul_f32_e32 v117, 0xbfb8aa3b, v169
	v_mul_f32_e32 v119, 0xbfb8aa3b, v121
	v_exp_f32_e32 v117, v117
	v_exp_f32_e32 v119, v119
	v_pk_mul_f32 v[112:113], v[112:113], v[166:167] op_sel_hi:[1,0]
	v_pk_mul_f32 v[170:171], v[170:171], v[166:167] op_sel_hi:[1,0]
	v_pk_mul_f32 v[122:123], v[122:123], v[166:167] op_sel_hi:[1,0]
	v_pk_mul_f32 v[172:173], v[172:173], v[166:167] op_sel_hi:[1,0]
	v_pk_mul_f32 v[174:175], v[174:175], v[166:167] op_sel_hi:[1,0]
	v_mul_f32_e32 v151, 0xbfb8aa3b, v113
	v_add_f32_e32 v117, 1.0, v117
	v_pk_mul_f32 v[114:115], v[114:115], v[166:167] op_sel_hi:[1,0]
	v_mul_f32_e32 v125, 0xbfb8aa3b, v171
	v_mul_f32_e32 v127, 0xbfb8aa3b, v123
	v_mul_f32_e32 v147, 0xbfb8aa3b, v173
	v_mul_f32_e32 v155, 0xbfb8aa3b, v175
	v_exp_f32_e32 v151, v151
	v_add_f32_e32 v119, 1.0, v119
	v_rcp_f32_e32 v117, v117
	v_mul_f32_e32 v159, 0xbfb8aa3b, v115
	v_exp_f32_e32 v125, v125
	v_exp_f32_e32 v127, v127
	v_exp_f32_e32 v147, v147
	v_exp_f32_e32 v155, v155
	v_rcp_f32_e32 v119, v119
	v_exp_f32_e32 v159, v159
	v_add_f32_e32 v151, 1.0, v151
	v_mul_f32_e32 v117, v169, v117
	v_add_f32_e32 v125, 1.0, v125
	v_add_f32_e32 v127, 1.0, v127
	v_add_f32_e32 v147, 1.0, v147
	v_add_f32_e32 v155, 1.0, v155
	v_rcp_f32_e32 v151, v151
	v_mul_f32_e32 v119, v121, v119
	v_mul_f32_e32 v117, v168, v117
	v_rcp_f32_e32 v125, v125
	v_rcp_f32_e32 v127, v127
	v_rcp_f32_e32 v147, v147
	v_rcp_f32_e32 v155, v155
	v_mul_f32_e32 v119, v120, v119
	v_cvt_pk_bf16_f32 v120, v117, v119
	v_add_f32_e32 v117, 1.0, v159
	v_rcp_f32_e32 v117, v117
	v_mul_f32_e32 v113, v113, v151
	v_mul_f32_e32 v121, v171, v125
	v_mul_f32_e32 v123, v123, v127
	v_mul_f32_e32 v125, v173, v147
	v_mul_f32_e32 v112, v112, v113
	v_mul_f32_e32 v113, v175, v155
	v_mul_f32_e32 v121, v170, v121
	v_mul_f32_e32 v122, v122, v123
	v_mul_f32_e32 v123, v172, v125
	v_mul_f32_e32 v113, v174, v113
	v_mul_f32_e32 v115, v115, v117
	v_cvt_pk_bf16_f32 v121, v121, v122
	v_mul_f32_e32 v114, v114, v115
	v_cvt_pk_bf16_f32 v122, v123, v112
	v_cvt_pk_bf16_f32 v123, v113, v114
	v_mov_b64_e32 v[112:113], s[64:65]
	v_mad_i64_i32 v[114:115], s[12:13], v164, s70, v[112:113]
	v_mov_b32_e32 v164, v104
	v_pk_mul_f32 v[164:165], v[164:165], v[180:181] op_sel_hi:[1,0]
	v_lshl_add_u64 v[114:115], v[114:115], 0, s[28:29]
	v_mul_f32_e32 v104, 0xbfb8aa3b, v165
	v_exp_f32_e32 v117, v104
	v_pk_mul_f32 v[104:105], v[108:109], v[180:181] op_sel_hi:[1,0]
	v_lshl_add_u64 v[114:115], v[114:115], 0, s[6:7]
	v_mul_f32_e32 v108, 0xbfb8aa3b, v105
	v_exp_f32_e32 v108, v108
	v_lshl_add_u64 v[114:115], v[114:115], 0, v[136:137]
	v_add_f32_e32 v109, 1.0, v117
	global_store_dwordx4 v[114:115], v[120:123], off sc0 sc1
	v_add_f32_e32 v108, 1.0, v108
	v_rcp_f32_e32 v114, v109
	v_rcp_f32_e32 v115, v108
	v_mov_b32_e32 v108, v106
	v_mov_b32_e32 v109, v110
	v_pk_mul_f32 v[108:109], v[108:109], v[180:181] op_sel_hi:[1,0]
	v_mul_f32_e32 v110, v165, v114
	v_mul_f32_e32 v106, 0xbfb8aa3b, v109
	v_exp_f32_e32 v106, v106
	v_mul_f32_e32 v114, v164, v110
	v_mov_b32_e32 v110, v107
	v_mul_f32_e32 v105, v105, v115
	v_add_f32_e32 v106, 1.0, v106
	v_rcp_f32_e32 v115, v106
	v_pk_mul_f32 v[106:107], v[110:111], v[180:181] op_sel_hi:[1,0]
	v_mul_f32_e32 v111, v104, v105
	v_mul_f32_e32 v110, 0xbfb8aa3b, v107
	v_exp_f32_e32 v110, v110
	v_mul_f32_e32 v104, v109, v115
	v_mul_f32_e32 v108, v108, v104
	v_mov_b32_e32 v105, v100
	v_add_f32_e32 v104, 1.0, v110
	v_rcp_f32_e32 v109, v104
	v_mov_b32_e32 v104, v96
	v_pk_mul_f32 v[104:105], v[104:105], v[180:181] op_sel_hi:[1,0]
	s_nop 0
	v_mul_f32_e32 v96, 0xbfb8aa3b, v105
	v_exp_f32_e32 v100, v96
	v_mul_f32_e32 v96, v107, v109
	v_mul_f32_e32 v106, v106, v96
	v_cvt_pk_bf16_f32 v96, v114, v111
	v_add_f32_e32 v100, 1.0, v100
	v_rcp_f32_e32 v107, v100
	v_mov_b32_e32 v100, v97
	v_pk_mul_f32 v[100:101], v[100:101], v[180:181] op_sel_hi:[1,0]
	v_mul_f32_e32 v105, v105, v107
	v_mul_f32_e32 v97, 0xbfb8aa3b, v101
	v_exp_f32_e32 v109, v97
	v_cvt_pk_bf16_f32 v97, v108, v106
	v_mul_f32_e32 v106, v104, v105
	v_mov_b32_e32 v105, v102
	v_add_f32_e32 v104, 1.0, v109
	v_rcp_f32_e32 v107, v104
	v_mov_b32_e32 v104, v98
	v_pk_mul_f32 v[104:105], v[104:105], v[180:181] op_sel_hi:[1,0]
	v_mov_b32_e32 v102, v99
	v_mul_f32_e32 v98, 0xbfb8aa3b, v105
	v_exp_f32_e32 v108, v98
	v_pk_mul_f32 v[98:99], v[102:103], v[180:181] op_sel_hi:[1,0]
	v_mul_f32_e32 v101, v101, v107
	v_mul_f32_e32 v102, 0xbfb8aa3b, v99
	v_exp_f32_e32 v102, v102
	v_add_f32_e32 v103, 1.0, v108
	v_rcp_f32_e32 v103, v103
	v_mul_f32_e32 v100, v100, v101
	v_add_f32_e32 v102, 1.0, v102
	v_rcp_f32_e32 v102, v102
	v_mul_f32_e32 v101, v105, v103
	v_mov_b32_e32 v103, v92
	v_mov_b32_e32 v92, v89
	v_mul_f32_e32 v99, v99, v102
	v_mov_b32_e32 v102, v88
	v_pk_mul_f32 v[102:103], v[102:103], v[160:161] op_sel_hi:[1,0]
	v_mul_f32_e32 v101, v104, v101
	v_mul_f32_e32 v88, 0xbfb8aa3b, v103
	v_exp_f32_e32 v104, v88
	v_pk_mul_f32 v[88:89], v[92:93], v[160:161] op_sel_hi:[1,0]
	v_mul_f32_e32 v99, v98, v99
	v_mul_f32_e32 v92, 0xbfb8aa3b, v89
	v_exp_f32_e32 v92, v92
	v_cvt_pk_bf16_f32 v98, v106, v100
	v_cvt_pk_bf16_f32 v99, v101, v99
	v_mad_i64_i32 v[100:101], s[12:13], v176, s70, v[112:113]
	v_lshl_add_u64 v[100:101], v[100:101], 0, s[28:29]
	v_lshl_add_u64 v[100:101], v[100:101], 0, s[6:7]
	v_lshl_add_u64 v[100:101], v[100:101], 0, v[136:137]
	v_add_f32_e32 v93, 1.0, v104
	v_add_f32_e32 v92, 1.0, v92
	global_store_dwordx4 v[100:101], v[96:99], off sc0 sc1
	s_nop 1
	v_rcp_f32_e32 v96, v93
	v_rcp_f32_e32 v97, v92
	v_mov_b32_e32 v92, v90
	v_mov_b32_e32 v93, v94
	v_pk_mul_f32 v[92:93], v[92:93], v[160:161] op_sel_hi:[1,0]
	v_mul_f32_e32 v94, v103, v96
	v_mul_f32_e32 v90, 0xbfb8aa3b, v93
	v_exp_f32_e32 v90, v90
	v_mul_f32_e32 v96, v102, v94
	v_mov_b32_e32 v94, v91
	v_mul_f32_e32 v89, v89, v97
	v_add_f32_e32 v90, 1.0, v90
	v_rcp_f32_e32 v97, v90
	v_pk_mul_f32 v[90:91], v[94:95], v[160:161] op_sel_hi:[1,0]
	v_mul_f32_e32 v95, v88, v89
	v_mul_f32_e32 v94, 0xbfb8aa3b, v91
	v_exp_f32_e32 v94, v94
	v_mul_f32_e32 v88, v93, v97
	v_mul_f32_e32 v92, v92, v88
	v_mov_b32_e32 v89, v84
	v_add_f32_e32 v88, 1.0, v94
	v_rcp_f32_e32 v93, v88
	v_mov_b32_e32 v88, v80
	v_pk_mul_f32 v[88:89], v[88:89], v[160:161] op_sel_hi:[1,0]
	s_nop 0
	v_mul_f32_e32 v80, 0xbfb8aa3b, v89
	v_exp_f32_e32 v84, v80
	v_mul_f32_e32 v80, v91, v93
	v_mul_f32_e32 v90, v90, v80
	v_cvt_pk_bf16_f32 v80, v96, v95
	v_add_f32_e32 v84, 1.0, v84
	v_rcp_f32_e32 v91, v84
	v_mov_b32_e32 v84, v81
	v_pk_mul_f32 v[84:85], v[84:85], v[160:161] op_sel_hi:[1,0]
	v_mul_f32_e32 v89, v89, v91
	v_mul_f32_e32 v81, 0xbfb8aa3b, v85
	v_exp_f32_e32 v93, v81
	v_cvt_pk_bf16_f32 v81, v92, v90
	v_mul_f32_e32 v90, v88, v89
	v_mov_b32_e32 v89, v86
	v_add_f32_e32 v88, 1.0, v93
	v_rcp_f32_e32 v91, v88
	v_mov_b32_e32 v88, v82
	v_pk_mul_f32 v[88:89], v[88:89], v[160:161] op_sel_hi:[1,0]
	v_mov_b32_e32 v86, v83
	v_mul_f32_e32 v82, 0xbfb8aa3b, v89
	v_exp_f32_e32 v92, v82
	v_pk_mul_f32 v[82:83], v[86:87], v[160:161] op_sel_hi:[1,0]
	v_mul_f32_e32 v85, v85, v91
	v_mul_f32_e32 v86, 0xbfb8aa3b, v83
	v_exp_f32_e32 v86, v86
	v_add_f32_e32 v87, 1.0, v92
	v_rcp_f32_e32 v87, v87
	v_mul_f32_e32 v84, v84, v85
	v_add_f32_e32 v86, 1.0, v86
	v_rcp_f32_e32 v86, v86
	v_mul_f32_e32 v85, v89, v87
	v_mov_b32_e32 v87, v76
	v_mov_b32_e32 v76, v73
	v_mul_f32_e32 v83, v83, v86
	v_mov_b32_e32 v86, v72
	v_pk_mul_f32 v[86:87], v[86:87], v[156:157] op_sel_hi:[1,0]
	v_mul_f32_e32 v85, v88, v85
	v_mul_f32_e32 v72, 0xbfb8aa3b, v87
	v_exp_f32_e32 v88, v72
	v_pk_mul_f32 v[72:73], v[76:77], v[156:157] op_sel_hi:[1,0]
	v_mul_f32_e32 v83, v82, v83
	v_mul_f32_e32 v76, 0xbfb8aa3b, v73
	v_exp_f32_e32 v76, v76
	v_cvt_pk_bf16_f32 v82, v90, v84
	v_cvt_pk_bf16_f32 v83, v85, v83
	v_mad_i64_i32 v[84:85], s[12:13], v158, s70, v[112:113]
	v_lshl_add_u64 v[84:85], v[84:85], 0, s[28:29]
	v_lshl_add_u64 v[84:85], v[84:85], 0, s[6:7]
	v_lshl_add_u64 v[84:85], v[84:85], 0, v[136:137]
	v_add_f32_e32 v77, 1.0, v88
	v_add_f32_e32 v76, 1.0, v76
	global_store_dwordx4 v[84:85], v[80:83], off sc0 sc1
	s_nop 1
	v_rcp_f32_e32 v80, v77
	v_rcp_f32_e32 v81, v76
	v_mov_b32_e32 v76, v74
	v_mov_b32_e32 v77, v78
	v_pk_mul_f32 v[76:77], v[76:77], v[156:157] op_sel_hi:[1,0]
	v_mul_f32_e32 v78, v87, v80
	v_mul_f32_e32 v74, 0xbfb8aa3b, v77
	v_exp_f32_e32 v74, v74
	v_mul_f32_e32 v80, v86, v78
	v_mov_b32_e32 v78, v75
	v_mul_f32_e32 v73, v73, v81
	v_add_f32_e32 v74, 1.0, v74
	v_rcp_f32_e32 v81, v74
	v_pk_mul_f32 v[74:75], v[78:79], v[156:157] op_sel_hi:[1,0]
	v_mul_f32_e32 v79, v72, v73
	v_mul_f32_e32 v78, 0xbfb8aa3b, v75
	v_exp_f32_e32 v78, v78
	v_mul_f32_e32 v72, v77, v81
	v_mul_f32_e32 v76, v76, v72
	v_mov_b32_e32 v73, v68
	v_add_f32_e32 v72, 1.0, v78
	v_rcp_f32_e32 v77, v72
	v_mov_b32_e32 v72, v64
	v_pk_mul_f32 v[72:73], v[72:73], v[156:157] op_sel_hi:[1,0]
	s_nop 0
	v_mul_f32_e32 v64, 0xbfb8aa3b, v73
	v_exp_f32_e32 v68, v64
	v_mul_f32_e32 v64, v75, v77
	v_mul_f32_e32 v74, v74, v64
	v_cvt_pk_bf16_f32 v64, v80, v79
	v_add_f32_e32 v68, 1.0, v68
	v_rcp_f32_e32 v75, v68
	v_mov_b32_e32 v68, v65
	v_pk_mul_f32 v[68:69], v[68:69], v[156:157] op_sel_hi:[1,0]
	v_mul_f32_e32 v73, v73, v75
	v_mul_f32_e32 v65, 0xbfb8aa3b, v69
	v_exp_f32_e32 v77, v65
	v_cvt_pk_bf16_f32 v65, v76, v74
	v_mul_f32_e32 v74, v72, v73
	v_mov_b32_e32 v73, v70
	v_add_f32_e32 v72, 1.0, v77
	v_rcp_f32_e32 v75, v72
	v_mov_b32_e32 v72, v66
	v_pk_mul_f32 v[72:73], v[72:73], v[156:157] op_sel_hi:[1,0]
	v_mov_b32_e32 v70, v67
	v_mul_f32_e32 v66, 0xbfb8aa3b, v73
	v_exp_f32_e32 v76, v66
	v_pk_mul_f32 v[66:67], v[70:71], v[156:157] op_sel_hi:[1,0]
	v_mul_f32_e32 v69, v69, v75
	v_mul_f32_e32 v70, 0xbfb8aa3b, v67
	v_exp_f32_e32 v70, v70
	v_add_f32_e32 v71, 1.0, v76
	v_rcp_f32_e32 v71, v71
	v_mul_f32_e32 v68, v68, v69
	v_add_f32_e32 v70, 1.0, v70
	v_rcp_f32_e32 v70, v70
	v_mul_f32_e32 v69, v73, v71
	v_mov_b32_e32 v71, v60
	v_mov_b32_e32 v60, v57
	v_mul_f32_e32 v67, v67, v70
	v_mov_b32_e32 v70, v56
	v_pk_mul_f32 v[70:71], v[70:71], v[152:153] op_sel_hi:[1,0]
	v_mul_f32_e32 v69, v72, v69
	v_mul_f32_e32 v56, 0xbfb8aa3b, v71
	v_exp_f32_e32 v72, v56
	v_pk_mul_f32 v[56:57], v[60:61], v[152:153] op_sel_hi:[1,0]
	v_mul_f32_e32 v67, v66, v67
	v_mul_f32_e32 v60, 0xbfb8aa3b, v57
	v_exp_f32_e32 v60, v60
	v_cvt_pk_bf16_f32 v66, v74, v68
	v_cvt_pk_bf16_f32 v67, v69, v67
	v_mad_i64_i32 v[68:69], s[12:13], v154, s70, v[112:113]
	v_lshl_add_u64 v[68:69], v[68:69], 0, s[28:29]
	v_lshl_add_u64 v[68:69], v[68:69], 0, s[6:7]
	v_lshl_add_u64 v[68:69], v[68:69], 0, v[136:137]
	v_add_f32_e32 v61, 1.0, v72
	v_add_f32_e32 v60, 1.0, v60
	global_store_dwordx4 v[68:69], v[64:67], off sc0 sc1
	s_nop 1
	v_rcp_f32_e32 v64, v61
	v_rcp_f32_e32 v65, v60
	v_mov_b32_e32 v60, v58
	v_mov_b32_e32 v61, v62
	v_pk_mul_f32 v[60:61], v[60:61], v[152:153] op_sel_hi:[1,0]
	v_mul_f32_e32 v62, v71, v64
	v_mul_f32_e32 v58, 0xbfb8aa3b, v61
	v_exp_f32_e32 v58, v58
	v_mul_f32_e32 v64, v70, v62
	v_mov_b32_e32 v62, v59
	v_mul_f32_e32 v57, v57, v65
	v_add_f32_e32 v58, 1.0, v58
	v_rcp_f32_e32 v65, v58
	v_pk_mul_f32 v[58:59], v[62:63], v[152:153] op_sel_hi:[1,0]
	v_mul_f32_e32 v63, v56, v57
	v_mul_f32_e32 v62, 0xbfb8aa3b, v59
	v_exp_f32_e32 v62, v62
	v_mul_f32_e32 v56, v61, v65
	v_mul_f32_e32 v60, v60, v56
	v_mov_b32_e32 v57, v52
	v_add_f32_e32 v56, 1.0, v62
	v_rcp_f32_e32 v61, v56
	v_mov_b32_e32 v56, v48
	v_pk_mul_f32 v[56:57], v[56:57], v[152:153] op_sel_hi:[1,0]
	s_nop 0
	v_mul_f32_e32 v48, 0xbfb8aa3b, v57
	v_exp_f32_e32 v52, v48
	v_mul_f32_e32 v48, v59, v61
	v_mul_f32_e32 v58, v58, v48
	v_cvt_pk_bf16_f32 v48, v64, v63
	v_add_f32_e32 v52, 1.0, v52
	v_rcp_f32_e32 v59, v52
	v_mov_b32_e32 v52, v49
	v_pk_mul_f32 v[52:53], v[52:53], v[152:153] op_sel_hi:[1,0]
	v_mul_f32_e32 v57, v57, v59
	v_mul_f32_e32 v49, 0xbfb8aa3b, v53
	v_exp_f32_e32 v61, v49
	v_cvt_pk_bf16_f32 v49, v60, v58
	v_mul_f32_e32 v58, v56, v57
	v_mov_b32_e32 v57, v54
	v_add_f32_e32 v56, 1.0, v61
	v_rcp_f32_e32 v59, v56
	v_mov_b32_e32 v56, v50
	v_pk_mul_f32 v[56:57], v[56:57], v[152:153] op_sel_hi:[1,0]
	v_mov_b32_e32 v54, v51
	v_mul_f32_e32 v50, 0xbfb8aa3b, v57
	v_exp_f32_e32 v60, v50
	v_pk_mul_f32 v[50:51], v[54:55], v[152:153] op_sel_hi:[1,0]
	v_mul_f32_e32 v53, v53, v59
	v_mul_f32_e32 v54, 0xbfb8aa3b, v51
	v_exp_f32_e32 v54, v54
	v_add_f32_e32 v55, 1.0, v60
	v_rcp_f32_e32 v55, v55
	v_mul_f32_e32 v52, v52, v53
	v_add_f32_e32 v54, 1.0, v54
	v_rcp_f32_e32 v54, v54
	v_mul_f32_e32 v53, v57, v55
	v_mov_b32_e32 v55, v44
	v_mov_b32_e32 v44, v41
	v_mul_f32_e32 v51, v51, v54
	v_mov_b32_e32 v54, v40
	v_pk_mul_f32 v[54:55], v[54:55], v[148:149] op_sel_hi:[1,0]
	v_mul_f32_e32 v53, v56, v53
	v_mul_f32_e32 v40, 0xbfb8aa3b, v55
	v_exp_f32_e32 v56, v40
	v_pk_mul_f32 v[40:41], v[44:45], v[148:149] op_sel_hi:[1,0]
	v_mul_f32_e32 v51, v50, v51
	v_mul_f32_e32 v44, 0xbfb8aa3b, v41
	v_exp_f32_e32 v44, v44
	v_cvt_pk_bf16_f32 v50, v58, v52
	v_cvt_pk_bf16_f32 v51, v53, v51
	v_mad_i64_i32 v[52:53], s[12:13], v150, s70, v[112:113]
	v_lshl_add_u64 v[52:53], v[52:53], 0, s[28:29]
	v_lshl_add_u64 v[52:53], v[52:53], 0, s[6:7]
	v_lshl_add_u64 v[52:53], v[52:53], 0, v[136:137]
	v_add_f32_e32 v45, 1.0, v56
	v_add_f32_e32 v44, 1.0, v44
	global_store_dwordx4 v[52:53], v[48:51], off sc0 sc1
	s_nop 1
	v_rcp_f32_e32 v48, v45
	v_rcp_f32_e32 v49, v44
	v_mov_b32_e32 v44, v42
	v_mov_b32_e32 v45, v46
	v_pk_mul_f32 v[44:45], v[44:45], v[148:149] op_sel_hi:[1,0]
	v_mul_f32_e32 v46, v55, v48
	v_mul_f32_e32 v42, 0xbfb8aa3b, v45
	v_exp_f32_e32 v42, v42
	v_mul_f32_e32 v48, v54, v46
	v_mov_b32_e32 v46, v43
	v_mul_f32_e32 v41, v41, v49
	v_add_f32_e32 v42, 1.0, v42
	v_rcp_f32_e32 v49, v42
	v_pk_mul_f32 v[42:43], v[46:47], v[148:149] op_sel_hi:[1,0]
	v_mul_f32_e32 v47, v40, v41
	v_mul_f32_e32 v46, 0xbfb8aa3b, v43
	v_exp_f32_e32 v46, v46
	v_mul_f32_e32 v40, v45, v49
	v_mul_f32_e32 v44, v44, v40
	v_mov_b32_e32 v41, v36
	v_add_f32_e32 v40, 1.0, v46
	v_rcp_f32_e32 v45, v40
	v_mov_b32_e32 v40, v32
	v_pk_mul_f32 v[40:41], v[40:41], v[148:149] op_sel_hi:[1,0]
	s_nop 0
	v_mul_f32_e32 v32, 0xbfb8aa3b, v41
	v_exp_f32_e32 v36, v32
	v_mul_f32_e32 v32, v43, v45
	v_mul_f32_e32 v42, v42, v32
	v_cvt_pk_bf16_f32 v32, v48, v47
	v_add_f32_e32 v36, 1.0, v36
	v_rcp_f32_e32 v43, v36
	v_mov_b32_e32 v36, v33
	v_pk_mul_f32 v[36:37], v[36:37], v[148:149] op_sel_hi:[1,0]
	v_mul_f32_e32 v41, v41, v43
	v_mul_f32_e32 v33, 0xbfb8aa3b, v37
	v_exp_f32_e32 v45, v33
	v_cvt_pk_bf16_f32 v33, v44, v42
	v_mul_f32_e32 v42, v40, v41
	v_mov_b32_e32 v41, v38
	v_add_f32_e32 v40, 1.0, v45
	v_rcp_f32_e32 v43, v40
	v_mov_b32_e32 v40, v34
	v_pk_mul_f32 v[40:41], v[40:41], v[148:149] op_sel_hi:[1,0]
	v_mov_b32_e32 v38, v35
	v_mul_f32_e32 v34, 0xbfb8aa3b, v41
	v_exp_f32_e32 v44, v34
	v_pk_mul_f32 v[34:35], v[38:39], v[148:149] op_sel_hi:[1,0]
	v_mul_f32_e32 v37, v37, v43
	v_mul_f32_e32 v38, 0xbfb8aa3b, v35
	v_exp_f32_e32 v38, v38
	v_add_f32_e32 v39, 1.0, v44
	v_rcp_f32_e32 v39, v39
	v_mul_f32_e32 v36, v36, v37
	v_add_f32_e32 v38, 1.0, v38
	v_rcp_f32_e32 v38, v38
	v_mul_f32_e32 v37, v41, v39
	v_mov_b32_e32 v39, v28
	v_mov_b32_e32 v28, v25
	v_mul_f32_e32 v35, v35, v38
	v_mov_b32_e32 v38, v24
	v_pk_mul_f32 v[38:39], v[38:39], v[126:127] op_sel_hi:[1,0]
	v_mul_f32_e32 v37, v40, v37
	v_mul_f32_e32 v24, 0xbfb8aa3b, v39
	v_exp_f32_e32 v40, v24
	v_pk_mul_f32 v[24:25], v[28:29], v[126:127] op_sel_hi:[1,0]
	v_mul_f32_e32 v35, v34, v35
	v_mul_f32_e32 v28, 0xbfb8aa3b, v25
	v_exp_f32_e32 v28, v28
	v_cvt_pk_bf16_f32 v34, v42, v36
	v_cvt_pk_bf16_f32 v35, v37, v35
	v_mad_i64_i32 v[36:37], s[12:13], v146, s70, v[112:113]
	v_lshl_add_u64 v[36:37], v[36:37], 0, s[28:29]
	v_lshl_add_u64 v[36:37], v[36:37], 0, s[6:7]
	v_lshl_add_u64 v[36:37], v[36:37], 0, v[136:137]
	v_add_f32_e32 v29, 1.0, v40
	v_add_f32_e32 v28, 1.0, v28
	global_store_dwordx4 v[36:37], v[32:35], off sc0 sc1
	s_nop 1
	v_rcp_f32_e32 v32, v29
	v_rcp_f32_e32 v33, v28
	v_mov_b32_e32 v28, v26
	v_mov_b32_e32 v29, v30
	v_pk_mul_f32 v[28:29], v[28:29], v[126:127] op_sel_hi:[1,0]
	v_mul_f32_e32 v30, v39, v32
	v_mul_f32_e32 v26, 0xbfb8aa3b, v29
	v_exp_f32_e32 v26, v26
	v_mul_f32_e32 v32, v38, v30
	v_mov_b32_e32 v30, v27
	v_mul_f32_e32 v25, v25, v33
	v_add_f32_e32 v26, 1.0, v26
	v_rcp_f32_e32 v33, v26
	v_pk_mul_f32 v[26:27], v[30:31], v[126:127] op_sel_hi:[1,0]
	v_mul_f32_e32 v31, v24, v25
	v_mul_f32_e32 v30, 0xbfb8aa3b, v27
	v_exp_f32_e32 v30, v30
	v_mul_f32_e32 v24, v29, v33
	v_mul_f32_e32 v28, v28, v24
	v_mov_b32_e32 v25, v20
	v_add_f32_e32 v24, 1.0, v30
	v_rcp_f32_e32 v29, v24
	v_mov_b32_e32 v24, v16
	v_pk_mul_f32 v[24:25], v[24:25], v[126:127] op_sel_hi:[1,0]
	s_nop 0
	v_mul_f32_e32 v16, 0xbfb8aa3b, v25
	v_exp_f32_e32 v20, v16
	v_mul_f32_e32 v16, v27, v29
	v_mul_f32_e32 v26, v26, v16
	v_cvt_pk_bf16_f32 v16, v32, v31
	v_add_f32_e32 v20, 1.0, v20
	v_rcp_f32_e32 v27, v20
	v_mov_b32_e32 v20, v17
	v_pk_mul_f32 v[20:21], v[20:21], v[126:127] op_sel_hi:[1,0]
	v_mul_f32_e32 v25, v25, v27
	v_mul_f32_e32 v17, 0xbfb8aa3b, v21
	v_exp_f32_e32 v29, v17
	v_cvt_pk_bf16_f32 v17, v28, v26
	v_mul_f32_e32 v26, v24, v25
	v_mov_b32_e32 v25, v22
	v_add_f32_e32 v24, 1.0, v29
	v_rcp_f32_e32 v27, v24
	v_mov_b32_e32 v24, v18
	v_pk_mul_f32 v[24:25], v[24:25], v[126:127] op_sel_hi:[1,0]
	v_mov_b32_e32 v22, v19
	v_mul_f32_e32 v18, 0xbfb8aa3b, v25
	v_exp_f32_e32 v28, v18
	v_pk_mul_f32 v[18:19], v[22:23], v[126:127] op_sel_hi:[1,0]
	v_mul_f32_e32 v21, v21, v27
	v_mul_f32_e32 v22, 0xbfb8aa3b, v19
	v_exp_f32_e32 v22, v22
	v_add_f32_e32 v23, 1.0, v28
	v_rcp_f32_e32 v23, v23
	v_mul_f32_e32 v20, v20, v21
	v_add_f32_e32 v22, 1.0, v22
	v_rcp_f32_e32 v22, v22
	v_mul_f32_e32 v21, v25, v23
	v_mov_b32_e32 v23, v12
	v_mov_b32_e32 v12, v9
	v_mul_f32_e32 v19, v19, v22
	v_mov_b32_e32 v22, v8
	v_pk_mul_f32 v[22:23], v[22:23], v[118:119] op_sel_hi:[1,0]
	v_mul_f32_e32 v21, v24, v21
	v_mul_f32_e32 v8, 0xbfb8aa3b, v23
	v_exp_f32_e32 v24, v8
	v_pk_mul_f32 v[8:9], v[12:13], v[118:119] op_sel_hi:[1,0]
	v_mul_f32_e32 v19, v18, v19
	v_mul_f32_e32 v12, 0xbfb8aa3b, v9
	v_exp_f32_e32 v12, v12
	v_cvt_pk_bf16_f32 v18, v26, v20
	v_cvt_pk_bf16_f32 v19, v21, v19
	v_mad_i64_i32 v[20:21], s[12:13], v124, s70, v[112:113]
	v_lshl_add_u64 v[20:21], v[20:21], 0, s[28:29]
	v_lshl_add_u64 v[20:21], v[20:21], 0, s[6:7]
	v_lshl_add_u64 v[20:21], v[20:21], 0, v[136:137]
	v_add_f32_e32 v13, 1.0, v24
	v_add_f32_e32 v12, 1.0, v12
	global_store_dwordx4 v[20:21], v[16:19], off sc0 sc1
	s_nop 1
	v_rcp_f32_e32 v16, v13
	v_rcp_f32_e32 v17, v12
	v_mov_b32_e32 v12, v10
	v_mov_b32_e32 v13, v14
	v_pk_mul_f32 v[12:13], v[12:13], v[118:119] op_sel_hi:[1,0]
	v_mul_f32_e32 v14, v23, v16
	v_mul_f32_e32 v10, 0xbfb8aa3b, v13
	v_exp_f32_e32 v10, v10
	v_mul_f32_e32 v16, v22, v14
	v_mov_b32_e32 v14, v11
	v_mul_f32_e32 v9, v9, v17
	v_add_f32_e32 v10, 1.0, v10
	v_rcp_f32_e32 v17, v10
	v_pk_mul_f32 v[10:11], v[14:15], v[118:119] op_sel_hi:[1,0]
	v_mul_f32_e32 v15, v8, v9
	v_mul_f32_e32 v14, 0xbfb8aa3b, v11
	v_exp_f32_e32 v14, v14
	v_mul_f32_e32 v8, v13, v17
	v_mul_f32_e32 v12, v12, v8
	v_mov_b32_e32 v9, v4
	v_add_f32_e32 v8, 1.0, v14
	v_rcp_f32_e32 v13, v8
	v_mov_b32_e32 v8, v0
	v_pk_mul_f32 v[8:9], v[8:9], v[118:119] op_sel_hi:[1,0]
	s_nop 0
	v_mul_f32_e32 v0, 0xbfb8aa3b, v9
	v_exp_f32_e32 v4, v0
	v_mul_f32_e32 v0, v11, v13
	v_mul_f32_e32 v10, v10, v0
	v_cvt_pk_bf16_f32 v0, v16, v15
	v_add_f32_e32 v4, 1.0, v4
	v_rcp_f32_e32 v11, v4
	v_mov_b32_e32 v4, v1
	v_pk_mul_f32 v[4:5], v[4:5], v[118:119] op_sel_hi:[1,0]
	v_mul_f32_e32 v9, v9, v11
	v_mul_f32_e32 v1, 0xbfb8aa3b, v5
	v_exp_f32_e32 v13, v1
	v_cvt_pk_bf16_f32 v1, v12, v10
	v_mul_f32_e32 v10, v8, v9
	v_mov_b32_e32 v9, v6
	v_add_f32_e32 v8, 1.0, v13
	v_rcp_f32_e32 v11, v8
	v_mov_b32_e32 v8, v2
	v_pk_mul_f32 v[8:9], v[8:9], v[118:119] op_sel_hi:[1,0]
	v_mov_b32_e32 v6, v3
	v_mul_f32_e32 v2, 0xbfb8aa3b, v9
	v_exp_f32_e32 v12, v2
	v_pk_mul_f32 v[2:3], v[6:7], v[118:119] op_sel_hi:[1,0]
	v_mul_f32_e32 v5, v5, v11
	v_mul_f32_e32 v6, 0xbfb8aa3b, v3
	v_exp_f32_e32 v6, v6
	v_add_f32_e32 v7, 1.0, v12
	v_rcp_f32_e32 v7, v7
	v_mul_f32_e32 v4, v4, v5
	v_add_f32_e32 v6, 1.0, v6
	v_rcp_f32_e32 v6, v6
	v_mul_f32_e32 v5, v9, v7
	v_mul_f32_e32 v5, v8, v5
	v_mul_f32_e32 v3, v3, v6
	v_mul_f32_e32 v3, v2, v3
	v_cvt_pk_bf16_f32 v2, v10, v4
	v_cvt_pk_bf16_f32 v3, v5, v3
	v_mad_i64_i32 v[4:5], s[12:13], v116, s70, v[112:113]
	v_lshl_add_u64 v[4:5], v[4:5], 0, s[28:29]
	v_lshl_add_u64 v[4:5], v[4:5], 0, s[6:7]
	v_lshl_add_u64 v[4:5], v[4:5], 0, v[136:137]
	global_store_dwordx4 v[4:5], v[0:3], off sc0 sc1
	s_cbranch_vccnz .LBB0_843
	s_andn2_b64 vcc, exec, s[8:9]
	s_cbranch_vccnz .LBB0_842
	s_barrier
	s_branch .LBB0_842

.LBB0_1745:
	v_lshl_add_u32 v166, s26, 8, v157
	v_ashrrev_i32_e32 v167, 31, v166
	v_lshl_add_u64 v[146:147], v[166:167], 2, s[66:67]
	v_mov_b32_e32 v168, v233
	v_or_b32_e32 v178, 16, v166
	v_ashrrev_i32_e32 v179, 31, v178
	v_mov_b32_e32 v176, v118
	v_mov_b32_e32 v177, v114
	v_mov_b32_e32 v114, v119
	v_lshl_add_u64 v[118:119], v[178:179], 2, s[66:67]
	v_mov_b32_e32 v182, v234
	v_or_b32_e32 v158, 32, v166
	v_add_u32_e32 v150, 0x80, v166
	v_mov_b32_e32 v170, v124
	v_mov_b32_e32 v171, v120
	v_mov_b32_e32 v174, v116
	v_or_b32_e32 v154, 48, v166
	v_add_u32_e32 v146, 0x90, v166
	v_add_u32_e32 v124, 0xa0, v166
	v_add_u32_e32 v116, 0xb0, v166
	v_ashrrev_i32_e32 v159, 31, v158
	v_ashrrev_i32_e32 v151, 31, v150
	v_mov_b32_e32 v120, v125
	v_mov_b32_e32 v172, v126
	v_mov_b32_e32 v173, v122
	v_mov_b32_e32 v122, v127
	v_mov_b32_e32 v175, v112
	v_mov_b32_e32 v112, v117
	v_ashrrev_i32_e32 v155, 31, v154
	v_ashrrev_i32_e32 v147, 31, v146
	v_ashrrev_i32_e32 v125, 31, v124
	v_ashrrev_i32_e32 v117, 31, v116
	v_lshl_add_u64 v[126:127], v[158:159], 2, s[66:67]
	v_lshl_add_u64 v[118:119], v[150:151], 2, s[66:67]
	v_lshl_add_u64 v[180:181], v[154:155], 2, s[66:67]
	v_lshl_add_u64 v[184:185], v[146:147], 2, s[66:67]
	v_lshl_add_u64 v[186:187], v[124:125], 2, s[66:67]
	v_lshl_add_u64 v[188:189], v[116:117], 2, s[66:67]
	v_mov_b32_e32 v160, v235
	v_mov_b32_e32 v156, v236
	v_mov_b32_e32 v152, v237
	v_mov_b32_e32 v148, v238
	s_nop 0
	v_mov_b32_e32 v126, v239
	v_mov_b32_e32 v118, v240
	s_cmp_lg_u64 s[4:5], 0
	s_cselect_b32 s92, s20, s26
	v_lshl_add_u32 v232, s92, 8, v157
	v_lshlrev_b32_e32 v232, 2, v232
	global_load_dword v233, v232, s[66:67]
	global_load_dword v234, v232, s[66:67] offset:64
	global_load_dword v235, v232, s[66:67] offset:128
	global_load_dword v236, v232, s[66:67] offset:192
	global_load_dword v237, v232, s[66:67] offset:512
	global_load_dword v238, v232, s[66:67] offset:576
	global_load_dword v239, v232, s[66:67] offset:640
	global_load_dword v240, v232, s[66:67] offset:704
	v_mov_b32_e32 v167, v108
	v_mov_b32_e32 v108, v105
	s_lshl_b32 s26, s27, 7
	s_ashr_i32 s27, s26, 31
	s_lshl_b64 s[26:27], s[26:27], 1
	s_andn2_b64 vcc, exec, s[4:5]
	s_mov_b64 s[4:5], -1
	v_pk_mul_f32 v[170:171], v[170:171], v[168:169] op_sel_hi:[1,0]
	v_pk_mul_f32 v[120:121], v[120:121], v[168:169] op_sel_hi:[1,0]
	v_mul_f32_e32 v117, 0xbfb8aa3b, v171
	v_mul_f32_e32 v119, 0xbfb8aa3b, v121
	v_exp_f32_e32 v117, v117
	v_exp_f32_e32 v119, v119
	v_pk_mul_f32 v[112:113], v[112:113], v[168:169] op_sel_hi:[1,0]
	v_pk_mul_f32 v[172:173], v[172:173], v[168:169] op_sel_hi:[1,0]
	v_pk_mul_f32 v[122:123], v[122:123], v[168:169] op_sel_hi:[1,0]
	v_pk_mul_f32 v[174:175], v[174:175], v[168:169] op_sel_hi:[1,0]
	v_pk_mul_f32 v[176:177], v[176:177], v[168:169] op_sel_hi:[1,0]
	v_mul_f32_e32 v151, 0xbfb8aa3b, v113
	v_add_f32_e32 v117, 1.0, v117
	v_pk_mul_f32 v[114:115], v[114:115], v[168:169] op_sel_hi:[1,0]
	v_mul_f32_e32 v125, 0xbfb8aa3b, v173
	v_mul_f32_e32 v127, 0xbfb8aa3b, v123
	v_mul_f32_e32 v147, 0xbfb8aa3b, v175
	v_mul_f32_e32 v155, 0xbfb8aa3b, v177
	v_exp_f32_e32 v151, v151
	v_add_f32_e32 v119, 1.0, v119
	v_rcp_f32_e32 v117, v117
	v_mul_f32_e32 v159, 0xbfb8aa3b, v115
	v_exp_f32_e32 v125, v125
	v_exp_f32_e32 v127, v127
	v_exp_f32_e32 v147, v147
	v_exp_f32_e32 v155, v155
	v_rcp_f32_e32 v119, v119
	v_exp_f32_e32 v159, v159
	v_add_f32_e32 v151, 1.0, v151
	v_mul_f32_e32 v117, v171, v117
	v_add_f32_e32 v125, 1.0, v125
	v_add_f32_e32 v127, 1.0, v127
	v_add_f32_e32 v147, 1.0, v147
	v_add_f32_e32 v155, 1.0, v155
	v_rcp_f32_e32 v151, v151
	v_mul_f32_e32 v119, v121, v119
	v_mul_f32_e32 v117, v170, v117
	v_rcp_f32_e32 v125, v125
	v_rcp_f32_e32 v127, v127
	v_rcp_f32_e32 v147, v147
	v_rcp_f32_e32 v155, v155
	v_mul_f32_e32 v119, v120, v119
	v_cvt_pk_bf16_f32 v120, v117, v119
	v_add_f32_e32 v117, 1.0, v159
	v_rcp_f32_e32 v117, v117
	v_mul_f32_e32 v113, v113, v151
	v_mul_f32_e32 v121, v173, v125
	v_mul_f32_e32 v123, v123, v127
	v_mul_f32_e32 v125, v175, v147
	v_mul_f32_e32 v112, v112, v113
	v_mul_f32_e32 v113, v177, v155
	v_mul_f32_e32 v121, v172, v121
	v_mul_f32_e32 v122, v122, v123
	v_mul_f32_e32 v123, v174, v125
	v_mul_f32_e32 v113, v176, v113
	v_mul_f32_e32 v115, v115, v117
	v_cvt_pk_bf16_f32 v121, v121, v122
	v_mul_f32_e32 v114, v114, v115
	v_cvt_pk_bf16_f32 v122, v123, v112
	v_cvt_pk_bf16_f32 v123, v113, v114
	v_mov_b64_e32 v[112:113], s[64:65]
	v_mad_i64_i32 v[114:115], s[12:13], v166, s52, v[112:113]
	v_mov_b32_e32 v166, v104
	v_pk_mul_f32 v[166:167], v[166:167], v[182:183] op_sel_hi:[1,0]
	v_lshl_add_u64 v[114:115], v[114:115], 0, s[26:27]
	v_mul_f32_e32 v104, 0xbfb8aa3b, v167
	v_exp_f32_e32 v117, v104
	v_pk_mul_f32 v[104:105], v[108:109], v[182:183] op_sel_hi:[1,0]
	v_lshl_add_u64 v[114:115], v[114:115], 0, s[6:7]
	v_mul_f32_e32 v108, 0xbfb8aa3b, v105
	v_exp_f32_e32 v108, v108
	v_lshl_add_u64 v[114:115], v[114:115], 0, v[136:137]
	v_add_f32_e32 v109, 1.0, v117
	global_store_dwordx4 v[114:115], v[120:123], off sc0 sc1
	v_add_f32_e32 v108, 1.0, v108
	v_rcp_f32_e32 v114, v109
	v_rcp_f32_e32 v115, v108
	v_mov_b32_e32 v108, v106
	v_mov_b32_e32 v109, v110
	v_pk_mul_f32 v[108:109], v[108:109], v[182:183] op_sel_hi:[1,0]
	v_mul_f32_e32 v110, v167, v114
	v_mul_f32_e32 v106, 0xbfb8aa3b, v109
	v_exp_f32_e32 v106, v106
	v_mul_f32_e32 v114, v166, v110
	v_mov_b32_e32 v110, v107
	v_mul_f32_e32 v105, v105, v115
	v_add_f32_e32 v106, 1.0, v106
	v_rcp_f32_e32 v115, v106
	v_pk_mul_f32 v[106:107], v[110:111], v[182:183] op_sel_hi:[1,0]
	v_mul_f32_e32 v111, v104, v105
	v_mul_f32_e32 v110, 0xbfb8aa3b, v107
	v_exp_f32_e32 v110, v110
	v_mul_f32_e32 v104, v109, v115
	v_mul_f32_e32 v108, v108, v104
	v_mov_b32_e32 v105, v100
	v_add_f32_e32 v104, 1.0, v110
	v_rcp_f32_e32 v109, v104
	v_mov_b32_e32 v104, v96
	v_pk_mul_f32 v[104:105], v[104:105], v[182:183] op_sel_hi:[1,0]
	s_nop 0
	v_mul_f32_e32 v96, 0xbfb8aa3b, v105
	v_exp_f32_e32 v100, v96
	v_mul_f32_e32 v96, v107, v109
	v_mul_f32_e32 v106, v106, v96
	v_cvt_pk_bf16_f32 v96, v114, v111
	v_add_f32_e32 v100, 1.0, v100
	v_rcp_f32_e32 v107, v100
	v_mov_b32_e32 v100, v97
	v_pk_mul_f32 v[100:101], v[100:101], v[182:183] op_sel_hi:[1,0]
	v_mul_f32_e32 v105, v105, v107
	v_mul_f32_e32 v97, 0xbfb8aa3b, v101
	v_exp_f32_e32 v109, v97
	v_cvt_pk_bf16_f32 v97, v108, v106
	v_mul_f32_e32 v106, v104, v105
	v_mov_b32_e32 v105, v102
	v_add_f32_e32 v104, 1.0, v109
	v_rcp_f32_e32 v107, v104
	v_mov_b32_e32 v104, v98
	v_pk_mul_f32 v[104:105], v[104:105], v[182:183] op_sel_hi:[1,0]
	v_mov_b32_e32 v102, v99
	v_mul_f32_e32 v98, 0xbfb8aa3b, v105
	v_exp_f32_e32 v108, v98
	v_pk_mul_f32 v[98:99], v[102:103], v[182:183] op_sel_hi:[1,0]
	v_mul_f32_e32 v101, v101, v107
	v_mul_f32_e32 v102, 0xbfb8aa3b, v99
	v_exp_f32_e32 v102, v102
	v_add_f32_e32 v103, 1.0, v108
	v_rcp_f32_e32 v103, v103
	v_mul_f32_e32 v100, v100, v101
	v_add_f32_e32 v102, 1.0, v102
	v_rcp_f32_e32 v102, v102
	v_mul_f32_e32 v101, v105, v103
	v_mov_b32_e32 v103, v92
	v_mov_b32_e32 v92, v89
	v_mul_f32_e32 v99, v99, v102
	v_mov_b32_e32 v102, v88
	v_pk_mul_f32 v[102:103], v[102:103], v[160:161] op_sel_hi:[1,0]
	v_mul_f32_e32 v101, v104, v101
	v_mul_f32_e32 v88, 0xbfb8aa3b, v103
	v_exp_f32_e32 v104, v88
	v_pk_mul_f32 v[88:89], v[92:93], v[160:161] op_sel_hi:[1,0]
	v_mul_f32_e32 v99, v98, v99
	v_mul_f32_e32 v92, 0xbfb8aa3b, v89
	v_exp_f32_e32 v92, v92
	v_cvt_pk_bf16_f32 v98, v106, v100
	v_cvt_pk_bf16_f32 v99, v101, v99
	v_mad_i64_i32 v[100:101], s[12:13], v178, s52, v[112:113]
	v_lshl_add_u64 v[100:101], v[100:101], 0, s[26:27]
	v_lshl_add_u64 v[100:101], v[100:101], 0, s[6:7]
	v_lshl_add_u64 v[100:101], v[100:101], 0, v[136:137]
	v_add_f32_e32 v93, 1.0, v104
	v_add_f32_e32 v92, 1.0, v92
	global_store_dwordx4 v[100:101], v[96:99], off sc0 sc1
	s_nop 1
	v_rcp_f32_e32 v96, v93
	v_rcp_f32_e32 v97, v92
	v_mov_b32_e32 v92, v90
	v_mov_b32_e32 v93, v94
	v_pk_mul_f32 v[92:93], v[92:93], v[160:161] op_sel_hi:[1,0]
	v_mul_f32_e32 v94, v103, v96
	v_mul_f32_e32 v90, 0xbfb8aa3b, v93
	v_exp_f32_e32 v90, v90
	v_mul_f32_e32 v96, v102, v94
	v_mov_b32_e32 v94, v91
	v_mul_f32_e32 v89, v89, v97
	v_add_f32_e32 v90, 1.0, v90
	v_rcp_f32_e32 v97, v90
	v_pk_mul_f32 v[90:91], v[94:95], v[160:161] op_sel_hi:[1,0]
	v_mul_f32_e32 v95, v88, v89
	v_mul_f32_e32 v94, 0xbfb8aa3b, v91
	v_exp_f32_e32 v94, v94
	v_mul_f32_e32 v88, v93, v97
	v_mul_f32_e32 v92, v92, v88
	v_mov_b32_e32 v89, v84
	v_add_f32_e32 v88, 1.0, v94
	v_rcp_f32_e32 v93, v88
	v_mov_b32_e32 v88, v80
	v_pk_mul_f32 v[88:89], v[88:89], v[160:161] op_sel_hi:[1,0]
	s_nop 0
	v_mul_f32_e32 v80, 0xbfb8aa3b, v89
	v_exp_f32_e32 v84, v80
	v_mul_f32_e32 v80, v91, v93
	v_mul_f32_e32 v90, v90, v80
	v_cvt_pk_bf16_f32 v80, v96, v95
	v_add_f32_e32 v84, 1.0, v84
	v_rcp_f32_e32 v91, v84
	v_mov_b32_e32 v84, v81
	v_pk_mul_f32 v[84:85], v[84:85], v[160:161] op_sel_hi:[1,0]
	v_mul_f32_e32 v89, v89, v91
	v_mul_f32_e32 v81, 0xbfb8aa3b, v85
	v_exp_f32_e32 v93, v81
	v_cvt_pk_bf16_f32 v81, v92, v90
	v_mul_f32_e32 v90, v88, v89
	v_mov_b32_e32 v89, v86
	v_add_f32_e32 v88, 1.0, v93
	v_rcp_f32_e32 v91, v88
	v_mov_b32_e32 v88, v82
	v_pk_mul_f32 v[88:89], v[88:89], v[160:161] op_sel_hi:[1,0]
	v_mov_b32_e32 v86, v83
	v_mul_f32_e32 v82, 0xbfb8aa3b, v89
	v_exp_f32_e32 v92, v82
	v_pk_mul_f32 v[82:83], v[86:87], v[160:161] op_sel_hi:[1,0]
	v_mul_f32_e32 v85, v85, v91
	v_mul_f32_e32 v86, 0xbfb8aa3b, v83
	v_exp_f32_e32 v86, v86
	v_add_f32_e32 v87, 1.0, v92
	v_rcp_f32_e32 v87, v87
	v_mul_f32_e32 v84, v84, v85
	v_add_f32_e32 v86, 1.0, v86
	v_rcp_f32_e32 v86, v86
	v_mul_f32_e32 v85, v89, v87
	v_mov_b32_e32 v87, v76
	v_mov_b32_e32 v76, v73
	v_mul_f32_e32 v83, v83, v86
	v_mov_b32_e32 v86, v72
	v_pk_mul_f32 v[86:87], v[86:87], v[156:157] op_sel_hi:[1,0]
	v_mul_f32_e32 v85, v88, v85
	v_mul_f32_e32 v72, 0xbfb8aa3b, v87
	v_exp_f32_e32 v88, v72
	v_pk_mul_f32 v[72:73], v[76:77], v[156:157] op_sel_hi:[1,0]
	v_mul_f32_e32 v83, v82, v83
	v_mul_f32_e32 v76, 0xbfb8aa3b, v73
	v_exp_f32_e32 v76, v76
	v_cvt_pk_bf16_f32 v82, v90, v84
	v_cvt_pk_bf16_f32 v83, v85, v83
	v_mad_i64_i32 v[84:85], s[12:13], v158, s52, v[112:113]
	v_lshl_add_u64 v[84:85], v[84:85], 0, s[26:27]
	v_lshl_add_u64 v[84:85], v[84:85], 0, s[6:7]
	v_lshl_add_u64 v[84:85], v[84:85], 0, v[136:137]
	v_add_f32_e32 v77, 1.0, v88
	v_add_f32_e32 v76, 1.0, v76
	global_store_dwordx4 v[84:85], v[80:83], off sc0 sc1
	s_nop 1
	v_rcp_f32_e32 v80, v77
	v_rcp_f32_e32 v81, v76
	v_mov_b32_e32 v76, v74
	v_mov_b32_e32 v77, v78
	v_pk_mul_f32 v[76:77], v[76:77], v[156:157] op_sel_hi:[1,0]
	v_mul_f32_e32 v78, v87, v80
	v_mul_f32_e32 v74, 0xbfb8aa3b, v77
	v_exp_f32_e32 v74, v74
	v_mul_f32_e32 v80, v86, v78
	v_mov_b32_e32 v78, v75
	v_mul_f32_e32 v73, v73, v81
	v_add_f32_e32 v74, 1.0, v74
	v_rcp_f32_e32 v81, v74
	v_pk_mul_f32 v[74:75], v[78:79], v[156:157] op_sel_hi:[1,0]
	v_mul_f32_e32 v79, v72, v73
	v_mul_f32_e32 v78, 0xbfb8aa3b, v75
	v_exp_f32_e32 v78, v78
	v_mul_f32_e32 v72, v77, v81
	v_mul_f32_e32 v76, v76, v72
	v_mov_b32_e32 v73, v68
	v_add_f32_e32 v72, 1.0, v78
	v_rcp_f32_e32 v77, v72
	v_mov_b32_e32 v72, v64
	v_pk_mul_f32 v[72:73], v[72:73], v[156:157] op_sel_hi:[1,0]
	s_nop 0
	v_mul_f32_e32 v64, 0xbfb8aa3b, v73
	v_exp_f32_e32 v68, v64
	v_mul_f32_e32 v64, v75, v77
	v_mul_f32_e32 v74, v74, v64
	v_cvt_pk_bf16_f32 v64, v80, v79
	v_add_f32_e32 v68, 1.0, v68
	v_rcp_f32_e32 v75, v68
	v_mov_b32_e32 v68, v65
	v_pk_mul_f32 v[68:69], v[68:69], v[156:157] op_sel_hi:[1,0]
	v_mul_f32_e32 v73, v73, v75
	v_mul_f32_e32 v65, 0xbfb8aa3b, v69
	v_exp_f32_e32 v77, v65
	v_cvt_pk_bf16_f32 v65, v76, v74
	v_mul_f32_e32 v74, v72, v73
	v_mov_b32_e32 v73, v70
	v_add_f32_e32 v72, 1.0, v77
	v_rcp_f32_e32 v75, v72
	v_mov_b32_e32 v72, v66
	v_pk_mul_f32 v[72:73], v[72:73], v[156:157] op_sel_hi:[1,0]
	v_mov_b32_e32 v70, v67
	v_mul_f32_e32 v66, 0xbfb8aa3b, v73
	v_exp_f32_e32 v76, v66
	v_pk_mul_f32 v[66:67], v[70:71], v[156:157] op_sel_hi:[1,0]
	v_mul_f32_e32 v69, v69, v75
	v_mul_f32_e32 v70, 0xbfb8aa3b, v67
	v_exp_f32_e32 v70, v70
	v_add_f32_e32 v71, 1.0, v76
	v_rcp_f32_e32 v71, v71
	v_mul_f32_e32 v68, v68, v69
	v_add_f32_e32 v70, 1.0, v70
	v_rcp_f32_e32 v70, v70
	v_mul_f32_e32 v69, v73, v71
	v_mov_b32_e32 v71, v60
	v_mov_b32_e32 v60, v57
	v_mul_f32_e32 v67, v67, v70
	v_mov_b32_e32 v70, v56
	v_pk_mul_f32 v[70:71], v[70:71], v[152:153] op_sel_hi:[1,0]
	v_mul_f32_e32 v69, v72, v69
	v_mul_f32_e32 v56, 0xbfb8aa3b, v71
	v_exp_f32_e32 v72, v56
	v_pk_mul_f32 v[56:57], v[60:61], v[152:153] op_sel_hi:[1,0]
	v_mul_f32_e32 v67, v66, v67
	v_mul_f32_e32 v60, 0xbfb8aa3b, v57
	v_exp_f32_e32 v60, v60
	v_cvt_pk_bf16_f32 v66, v74, v68
	v_cvt_pk_bf16_f32 v67, v69, v67
	v_mad_i64_i32 v[68:69], s[12:13], v154, s52, v[112:113]
	v_lshl_add_u64 v[68:69], v[68:69], 0, s[26:27]
	v_lshl_add_u64 v[68:69], v[68:69], 0, s[6:7]
	v_lshl_add_u64 v[68:69], v[68:69], 0, v[136:137]
	v_add_f32_e32 v61, 1.0, v72
	v_add_f32_e32 v60, 1.0, v60
	global_store_dwordx4 v[68:69], v[64:67], off sc0 sc1
	s_nop 1
	v_rcp_f32_e32 v64, v61
	v_rcp_f32_e32 v65, v60
	v_mov_b32_e32 v60, v58
	v_mov_b32_e32 v61, v62
	v_pk_mul_f32 v[60:61], v[60:61], v[152:153] op_sel_hi:[1,0]
	v_mul_f32_e32 v62, v71, v64
	v_mul_f32_e32 v58, 0xbfb8aa3b, v61
	v_exp_f32_e32 v58, v58
	v_mul_f32_e32 v64, v70, v62
	v_mov_b32_e32 v62, v59
	v_mul_f32_e32 v57, v57, v65
	v_add_f32_e32 v58, 1.0, v58
	v_rcp_f32_e32 v65, v58
	v_pk_mul_f32 v[58:59], v[62:63], v[152:153] op_sel_hi:[1,0]
	v_mul_f32_e32 v63, v56, v57
	v_mul_f32_e32 v62, 0xbfb8aa3b, v59
	v_exp_f32_e32 v62, v62
	v_mul_f32_e32 v56, v61, v65
	v_mul_f32_e32 v60, v60, v56
	v_mov_b32_e32 v57, v52
	v_add_f32_e32 v56, 1.0, v62
	v_rcp_f32_e32 v61, v56
	v_mov_b32_e32 v56, v48
	v_pk_mul_f32 v[56:57], v[56:57], v[152:153] op_sel_hi:[1,0]
	s_nop 0
	v_mul_f32_e32 v48, 0xbfb8aa3b, v57
	v_exp_f32_e32 v52, v48
	v_mul_f32_e32 v48, v59, v61
	v_mul_f32_e32 v58, v58, v48
	v_cvt_pk_bf16_f32 v48, v64, v63
	v_add_f32_e32 v52, 1.0, v52
	v_rcp_f32_e32 v59, v52
	v_mov_b32_e32 v52, v49
	v_pk_mul_f32 v[52:53], v[52:53], v[152:153] op_sel_hi:[1,0]
	v_mul_f32_e32 v57, v57, v59
	v_mul_f32_e32 v49, 0xbfb8aa3b, v53
	v_exp_f32_e32 v61, v49
	v_cvt_pk_bf16_f32 v49, v60, v58
	v_mul_f32_e32 v58, v56, v57
	v_mov_b32_e32 v57, v54
	v_add_f32_e32 v56, 1.0, v61
	v_rcp_f32_e32 v59, v56
	v_mov_b32_e32 v56, v50
	v_pk_mul_f32 v[56:57], v[56:57], v[152:153] op_sel_hi:[1,0]
	v_mov_b32_e32 v54, v51
	v_mul_f32_e32 v50, 0xbfb8aa3b, v57
	v_exp_f32_e32 v60, v50
	v_pk_mul_f32 v[50:51], v[54:55], v[152:153] op_sel_hi:[1,0]
	v_mul_f32_e32 v53, v53, v59
	v_mul_f32_e32 v54, 0xbfb8aa3b, v51
	v_exp_f32_e32 v54, v54
	v_add_f32_e32 v55, 1.0, v60
	v_rcp_f32_e32 v55, v55
	v_mul_f32_e32 v52, v52, v53
	v_add_f32_e32 v54, 1.0, v54
	v_rcp_f32_e32 v54, v54
	v_mul_f32_e32 v53, v57, v55
	v_mov_b32_e32 v55, v44
	v_mov_b32_e32 v44, v41
	v_mul_f32_e32 v51, v51, v54
	v_mov_b32_e32 v54, v40
	v_pk_mul_f32 v[54:55], v[54:55], v[148:149] op_sel_hi:[1,0]
	v_mul_f32_e32 v53, v56, v53
	v_mul_f32_e32 v40, 0xbfb8aa3b, v55
	v_exp_f32_e32 v56, v40
	v_pk_mul_f32 v[40:41], v[44:45], v[148:149] op_sel_hi:[1,0]
	v_mul_f32_e32 v51, v50, v51
	v_mul_f32_e32 v44, 0xbfb8aa3b, v41
	v_exp_f32_e32 v44, v44
	v_cvt_pk_bf16_f32 v50, v58, v52
	v_cvt_pk_bf16_f32 v51, v53, v51
	v_mad_i64_i32 v[52:53], s[12:13], v150, s52, v[112:113]
	v_lshl_add_u64 v[52:53], v[52:53], 0, s[26:27]
	v_lshl_add_u64 v[52:53], v[52:53], 0, s[6:7]
	v_lshl_add_u64 v[52:53], v[52:53], 0, v[136:137]
	v_add_f32_e32 v45, 1.0, v56
	v_add_f32_e32 v44, 1.0, v44
	global_store_dwordx4 v[52:53], v[48:51], off sc0 sc1
	s_nop 1
	v_rcp_f32_e32 v48, v45
	v_rcp_f32_e32 v49, v44
	v_mov_b32_e32 v44, v42
	v_mov_b32_e32 v45, v46
	v_pk_mul_f32 v[44:45], v[44:45], v[148:149] op_sel_hi:[1,0]
	v_mul_f32_e32 v46, v55, v48
	v_mul_f32_e32 v42, 0xbfb8aa3b, v45
	v_exp_f32_e32 v42, v42
	v_mul_f32_e32 v48, v54, v46
	v_mov_b32_e32 v46, v43
	v_mul_f32_e32 v41, v41, v49
	v_add_f32_e32 v42, 1.0, v42
	v_rcp_f32_e32 v49, v42
	v_pk_mul_f32 v[42:43], v[46:47], v[148:149] op_sel_hi:[1,0]
	v_mul_f32_e32 v47, v40, v41
	v_mul_f32_e32 v46, 0xbfb8aa3b, v43
	v_exp_f32_e32 v46, v46
	v_mul_f32_e32 v40, v45, v49
	v_mul_f32_e32 v44, v44, v40
	v_mov_b32_e32 v41, v36
	v_add_f32_e32 v40, 1.0, v46
	v_rcp_f32_e32 v45, v40
	v_mov_b32_e32 v40, v32
	v_pk_mul_f32 v[40:41], v[40:41], v[148:149] op_sel_hi:[1,0]
	s_nop 0
	v_mul_f32_e32 v32, 0xbfb8aa3b, v41
	v_exp_f32_e32 v36, v32
	v_mul_f32_e32 v32, v43, v45
	v_mul_f32_e32 v42, v42, v32
	v_cvt_pk_bf16_f32 v32, v48, v47
	v_add_f32_e32 v36, 1.0, v36
	v_rcp_f32_e32 v43, v36
	v_mov_b32_e32 v36, v33
	v_pk_mul_f32 v[36:37], v[36:37], v[148:149] op_sel_hi:[1,0]
	v_mul_f32_e32 v41, v41, v43
	v_mul_f32_e32 v33, 0xbfb8aa3b, v37
	v_exp_f32_e32 v45, v33
	v_cvt_pk_bf16_f32 v33, v44, v42
	v_mul_f32_e32 v42, v40, v41
	v_mov_b32_e32 v41, v38
	v_add_f32_e32 v40, 1.0, v45
	v_rcp_f32_e32 v43, v40
	v_mov_b32_e32 v40, v34
	v_pk_mul_f32 v[40:41], v[40:41], v[148:149] op_sel_hi:[1,0]
	v_mov_b32_e32 v38, v35
	v_mul_f32_e32 v34, 0xbfb8aa3b, v41
	v_exp_f32_e32 v44, v34
	v_pk_mul_f32 v[34:35], v[38:39], v[148:149] op_sel_hi:[1,0]
	v_mul_f32_e32 v37, v37, v43
	v_mul_f32_e32 v38, 0xbfb8aa3b, v35
	v_exp_f32_e32 v38, v38
	v_add_f32_e32 v39, 1.0, v44
	v_rcp_f32_e32 v39, v39
	v_mul_f32_e32 v36, v36, v37
	v_add_f32_e32 v38, 1.0, v38
	v_rcp_f32_e32 v38, v38
	v_mul_f32_e32 v37, v41, v39
	v_mov_b32_e32 v39, v28
	v_mov_b32_e32 v28, v25
	v_mul_f32_e32 v35, v35, v38
	v_mov_b32_e32 v38, v24
	v_pk_mul_f32 v[38:39], v[38:39], v[126:127] op_sel_hi:[1,0]
	v_mul_f32_e32 v37, v40, v37
	v_mul_f32_e32 v24, 0xbfb8aa3b, v39
	v_exp_f32_e32 v40, v24
	v_pk_mul_f32 v[24:25], v[28:29], v[126:127] op_sel_hi:[1,0]
	v_mul_f32_e32 v35, v34, v35
	v_mul_f32_e32 v28, 0xbfb8aa3b, v25
	v_exp_f32_e32 v28, v28
	v_cvt_pk_bf16_f32 v34, v42, v36
	v_cvt_pk_bf16_f32 v35, v37, v35
	v_mad_i64_i32 v[36:37], s[12:13], v146, s52, v[112:113]
	v_lshl_add_u64 v[36:37], v[36:37], 0, s[26:27]
	v_lshl_add_u64 v[36:37], v[36:37], 0, s[6:7]
	v_lshl_add_u64 v[36:37], v[36:37], 0, v[136:137]
	v_add_f32_e32 v29, 1.0, v40
	v_add_f32_e32 v28, 1.0, v28
	global_store_dwordx4 v[36:37], v[32:35], off sc0 sc1
	s_nop 1
	v_rcp_f32_e32 v32, v29
	v_rcp_f32_e32 v33, v28
	v_mov_b32_e32 v28, v26
	v_mov_b32_e32 v29, v30
	v_pk_mul_f32 v[28:29], v[28:29], v[126:127] op_sel_hi:[1,0]
	v_mul_f32_e32 v30, v39, v32
	v_mul_f32_e32 v26, 0xbfb8aa3b, v29
	v_exp_f32_e32 v26, v26
	v_mul_f32_e32 v32, v38, v30
	v_mov_b32_e32 v30, v27
	v_mul_f32_e32 v25, v25, v33
	v_add_f32_e32 v26, 1.0, v26
	v_rcp_f32_e32 v33, v26
	v_pk_mul_f32 v[26:27], v[30:31], v[126:127] op_sel_hi:[1,0]
	v_mul_f32_e32 v31, v24, v25
	v_mul_f32_e32 v30, 0xbfb8aa3b, v27
	v_exp_f32_e32 v30, v30
	v_mul_f32_e32 v24, v29, v33
	v_mul_f32_e32 v28, v28, v24
	v_mov_b32_e32 v25, v20
	v_add_f32_e32 v24, 1.0, v30
	v_rcp_f32_e32 v29, v24
	v_mov_b32_e32 v24, v16
	v_pk_mul_f32 v[24:25], v[24:25], v[126:127] op_sel_hi:[1,0]
	s_nop 0
	v_mul_f32_e32 v16, 0xbfb8aa3b, v25
	v_exp_f32_e32 v20, v16
	v_mul_f32_e32 v16, v27, v29
	v_mul_f32_e32 v26, v26, v16
	v_cvt_pk_bf16_f32 v16, v32, v31
	v_add_f32_e32 v20, 1.0, v20
	v_rcp_f32_e32 v27, v20
	v_mov_b32_e32 v20, v17
	v_pk_mul_f32 v[20:21], v[20:21], v[126:127] op_sel_hi:[1,0]
	v_mul_f32_e32 v25, v25, v27
	v_mul_f32_e32 v17, 0xbfb8aa3b, v21
	v_exp_f32_e32 v29, v17
	v_cvt_pk_bf16_f32 v17, v28, v26
	v_mul_f32_e32 v26, v24, v25
	v_mov_b32_e32 v25, v22
	v_add_f32_e32 v24, 1.0, v29
	v_rcp_f32_e32 v27, v24
	v_mov_b32_e32 v24, v18
	v_pk_mul_f32 v[24:25], v[24:25], v[126:127] op_sel_hi:[1,0]
	v_mov_b32_e32 v22, v19
	v_mul_f32_e32 v18, 0xbfb8aa3b, v25
	v_exp_f32_e32 v28, v18
	v_pk_mul_f32 v[18:19], v[22:23], v[126:127] op_sel_hi:[1,0]
	v_mul_f32_e32 v21, v21, v27
	v_mul_f32_e32 v22, 0xbfb8aa3b, v19
	v_exp_f32_e32 v22, v22
	v_add_f32_e32 v23, 1.0, v28
	v_rcp_f32_e32 v23, v23
	v_mul_f32_e32 v20, v20, v21
	v_add_f32_e32 v22, 1.0, v22
	v_rcp_f32_e32 v22, v22
	v_mul_f32_e32 v21, v25, v23
	v_mov_b32_e32 v23, v12
	v_mov_b32_e32 v12, v9
	v_mul_f32_e32 v19, v19, v22
	v_mov_b32_e32 v22, v8
	v_pk_mul_f32 v[22:23], v[22:23], v[118:119] op_sel_hi:[1,0]
	v_mul_f32_e32 v21, v24, v21
	v_mul_f32_e32 v8, 0xbfb8aa3b, v23
	v_exp_f32_e32 v24, v8
	v_pk_mul_f32 v[8:9], v[12:13], v[118:119] op_sel_hi:[1,0]
	v_mul_f32_e32 v19, v18, v19
	v_mul_f32_e32 v12, 0xbfb8aa3b, v9
	v_exp_f32_e32 v12, v12
	v_cvt_pk_bf16_f32 v18, v26, v20
	v_cvt_pk_bf16_f32 v19, v21, v19
	v_mad_i64_i32 v[20:21], s[12:13], v124, s52, v[112:113]
	v_lshl_add_u64 v[20:21], v[20:21], 0, s[26:27]
	v_lshl_add_u64 v[20:21], v[20:21], 0, s[6:7]
	v_lshl_add_u64 v[20:21], v[20:21], 0, v[136:137]
	v_add_f32_e32 v13, 1.0, v24
	v_add_f32_e32 v12, 1.0, v12
	global_store_dwordx4 v[20:21], v[16:19], off sc0 sc1
	s_nop 1
	v_rcp_f32_e32 v16, v13
	v_rcp_f32_e32 v17, v12
	v_mov_b32_e32 v12, v10
	v_mov_b32_e32 v13, v14
	v_pk_mul_f32 v[12:13], v[12:13], v[118:119] op_sel_hi:[1,0]
	v_mul_f32_e32 v14, v23, v16
	v_mul_f32_e32 v10, 0xbfb8aa3b, v13
	v_exp_f32_e32 v10, v10
	v_mul_f32_e32 v16, v22, v14
	v_mov_b32_e32 v14, v11
	v_mul_f32_e32 v9, v9, v17
	v_add_f32_e32 v10, 1.0, v10
	v_rcp_f32_e32 v17, v10
	v_pk_mul_f32 v[10:11], v[14:15], v[118:119] op_sel_hi:[1,0]
	v_mul_f32_e32 v15, v8, v9
	v_mul_f32_e32 v14, 0xbfb8aa3b, v11
	v_exp_f32_e32 v14, v14
	v_mul_f32_e32 v8, v13, v17
	v_mul_f32_e32 v12, v12, v8
	v_mov_b32_e32 v9, v4
	v_add_f32_e32 v8, 1.0, v14
	v_rcp_f32_e32 v13, v8
	v_mov_b32_e32 v8, v0
	v_pk_mul_f32 v[8:9], v[8:9], v[118:119] op_sel_hi:[1,0]
	s_nop 0
	v_mul_f32_e32 v0, 0xbfb8aa3b, v9
	v_exp_f32_e32 v4, v0
	v_mul_f32_e32 v0, v11, v13
	v_mul_f32_e32 v10, v10, v0
	v_cvt_pk_bf16_f32 v0, v16, v15
	v_add_f32_e32 v4, 1.0, v4
	v_rcp_f32_e32 v11, v4
	v_mov_b32_e32 v4, v1
	v_pk_mul_f32 v[4:5], v[4:5], v[118:119] op_sel_hi:[1,0]
	v_mul_f32_e32 v9, v9, v11
	v_mul_f32_e32 v1, 0xbfb8aa3b, v5
	v_exp_f32_e32 v13, v1
	v_cvt_pk_bf16_f32 v1, v12, v10
	v_mul_f32_e32 v10, v8, v9
	v_mov_b32_e32 v9, v6
	v_add_f32_e32 v8, 1.0, v13
	v_rcp_f32_e32 v11, v8
	v_mov_b32_e32 v8, v2
	v_pk_mul_f32 v[8:9], v[8:9], v[118:119] op_sel_hi:[1,0]
	v_mov_b32_e32 v6, v3
	v_mul_f32_e32 v2, 0xbfb8aa3b, v9
	v_exp_f32_e32 v12, v2
	v_pk_mul_f32 v[2:3], v[6:7], v[118:119] op_sel_hi:[1,0]
	v_mul_f32_e32 v5, v5, v11
	v_mul_f32_e32 v6, 0xbfb8aa3b, v3
	v_exp_f32_e32 v6, v6
	v_add_f32_e32 v7, 1.0, v12
	v_rcp_f32_e32 v7, v7
	v_mul_f32_e32 v4, v4, v5
	v_add_f32_e32 v6, 1.0, v6
	v_rcp_f32_e32 v6, v6
	v_mul_f32_e32 v5, v9, v7
	v_mul_f32_e32 v5, v8, v5
	v_mul_f32_e32 v3, v3, v6
	v_mul_f32_e32 v3, v2, v3
	v_cvt_pk_bf16_f32 v2, v10, v4
	v_cvt_pk_bf16_f32 v3, v5, v3
	v_mad_i64_i32 v[4:5], s[12:13], v116, s52, v[112:113]
	v_lshl_add_u64 v[4:5], v[4:5], 0, s[26:27]
	v_lshl_add_u64 v[4:5], v[4:5], 0, s[6:7]
	v_lshl_add_u64 v[4:5], v[4:5], 0, v[136:137]
	global_store_dwordx4 v[4:5], v[0:3], off sc0 sc1
	s_cbranch_vccnz .LBB0_1738
	s_andn2_b64 vcc, exec, s[8:9]
	s_cbranch_vccnz .LBB0_1737
	s_barrier
	s_branch .LBB0_1737
